# v12 + attention loop: dropped the 3 WG barriers that only ordered wave-private P/O LDS rows (2 barriers per item remain)
# speedup vs baseline: 1.0105x; 1.0087x over previous
; __device__ __forceinline__ bf16_t f2bf(float f) { return (bf16_t)(cvt_pk_bf16(f, 0.f) & 0xffffu); }
; __device__ void attn_items(const Params& p, unsigned char* shm) {
;     ...
; #pragma unroll
;         for (int i = 0; i < 4; ++i) { const float inv = 1.0f / ls[i];
; #pragma unroll
;             for (int nt = 0; nt < 4; ++nt) Pw[(fq * 4 + i) * 168 + nt * 16 + fr] = f2bf(o[nt][i] * inv);
;             if (fr == 0) LSE[(size_t)(G.seq_start + G.r + G.dil * (G.q0 + 16 * w + fq * 4 + i)) * 24 + G.hd] = mx[i] + __logf(ls[i]); }
;         __syncthreads();
; #pragma unroll
;         for (int h = 0; h < 2; ++h) { const int c = lane + 64 * h, row = c >> 3, c8 = c & 7;
;             *(u32x4*)(Qb + (size_t)(G.seq_start + G.r + G.dil * (G.q0 + 16 * w + row)) * 1536 + G.hd * 64 + c8 * 8) = *(const u32x4*)(Pw + row * 168 + c8 * 8); }
;         __syncthreads();
.LBB0_340:
	s_or_b64 exec, exec, s[0:1]
	s_waitcnt lgkmcnt(0)
	ds_read_b128 v[52:55], v173
	s_lshl_b32 s0, s58, 6
	v_or_b32_e32 v56, v0, v109
	s_ashr_i32 s1, s0, 31
	v_lshlrev_b32_e32 v56, s4, v56
	v_lshl_add_u64 v[2:3], s[0:1], 1, v[94:95]
	v_add_u32_e32 v56, s6, v56
	s_movk_i32 s5, 0xc00
	v_mad_i64_i32 v[56:57], s[0:1], v56, s5, v[2:3]
	s_waitcnt lgkmcnt(0)
	global_store_dwordx4 v[56:57], v[52:55], off
	ds_read_b128 v[52:55], v174
	v_or_b32_e32 v0, v0, v149
	v_lshlrev_b32_e32 v0, s4, v0
	v_add_u32_e32 v0, s6, v0
	v_mad_i64_i32 v[2:3], s[0:1], v0, s5, v[2:3]
	s_waitcnt lgkmcnt(0)
	global_store_dwordx4 v[2:3], v[52:55], off
	s_waitcnt vmcnt(3)
	v_mov_b64_e32 v[58:59], v[46:47]
	s_movk_i32 s22, 0xc00
	s_waitcnt vmcnt(2)
	v_mov_b64_e32 v[54:55], v[50:51]
	s_add_i32 s2, s2, s3
	s_and_b64 vcc, exec, s[40:41]
	v_mov_b64_e32 v[56:57], v[44:45]
	v_mov_b64_e32 v[52:53], v[48:49]
	s_mov_b32 s4, s15
	s_barrier
	s_cbranch_vccnz .LBB0_793

; __device__ void attn_items(const Params& p, unsigned char* shm) {
;     ...
;         const float* bs = BT + G.hd * 132;
;         f32x4 s[9];
; #pragma unroll
;         for (int kt = 0; kt < 9; ++kt) { const bf16_t* kr = Ks + (16 * w + 16 * kt + fr) * 72 + fq * 8;
;             f32x4 a = (f32x4){0.f, 0.f, 0.f, 0.f};
;             a = __builtin_amdgcn_mfma_f32_16x16x32_bf16(aq0, *(const bf16x8*)kr, a, 0, 0, 0);
;             a = __builtin_amdgcn_mfma_f32_16x16x32_bf16(aq1, *(const bf16x8*)(kr + 32), a, 0, 0, 0); s[kt] = a; }
;         float mx[4], ls[4];
; #pragma unroll
;         for (int i = 0; i < 4; ++i) { const int qi = fq * 4 + i; float m = -3.0e38f;
; #pragma unroll
;             for (int kt = 0; kt < 9; ++kt) { const int rel = 16 * kt + fr - 64 - qi, klat = G.q0 - 64 + 16 * w + 16 * kt + fr;
;                 const bool ok = rel >= -64 && rel <= 64 && klat >= 0 && klat < G.n_lat; const int bi = min(max(rel + 64, 0), 128);
;                 const float v = ok ? s[kt][i] + bs[bi] : -1.0e30f; s[kt][i] = v; m = fmaxf(m, v); }
.LBB0_373:
	v_add_u32_e32 v0, v101, v114
	ds_read_b128 v[60:63], v0
	ds_read_b128 v[64:67], v0 offset:64
	s_mul_hi_i32 s0, s4, 0x2aaaaaab
	s_lshr_b32 s1, s0, 31
	s_waitcnt lgkmcnt(1)
	v_mfma_f32_16x16x32_bf16 v[60:63], v[56:59], v[60:63], 0
	s_ashr_i32 s0, s0, 5
	s_add_i32 s58, s0, s1
	ds_read_b128 v[68:71], v164 offset:64
	s_waitcnt lgkmcnt(1)
	v_mfma_f32_16x16x32_bf16 v[60:63], v[52:55], v[64:67], v[60:63]
	ds_read_b128 v[64:67], v164
	s_mul_i32 s0, s58, 0xffffff40
	s_add_i32 s0, s4, s0
	s_waitcnt lgkmcnt(0)
	v_mfma_f32_16x16x32_bf16 v[64:67], v[56:59], v[64:67], 0
	s_and_b32 s4, s0, 15
	ds_read_b128 v[72:75], v165 offset:64
	s_sub_i32 s5, s0, 64
	v_mfma_f32_16x16x32_bf16 v[64:67], v[52:55], v[68:71], v[64:67]
	ds_read_b128 v[68:71], v165
	s_cmp_lt_i32 s0, 64
	s_cselect_b64 s[60:61], -1, 0
	s_waitcnt lgkmcnt(0)
	v_mfma_f32_16x16x32_bf16 v[68:71], v[56:59], v[68:71], 0
	ds_read_b128 v[76:79], v166 offset:64
	s_and_b64 s[0:1], s[60:61], exec
	s_movk_i32 s0, 0x800
	v_mfma_f32_16x16x32_bf16 v[68:71], v[52:55], v[72:75], v[68:71]
	ds_read_b128 v[72:75], v166
	s_cselect_b32 s6, s4, s5
	s_cselect_b32 s0, s0, 0x4000
	s_waitcnt lgkmcnt(0)
	v_mfma_f32_16x16x32_bf16 v[72:75], v[56:59], v[72:75], 0
	ds_read_b128 v[80:83], v167 offset:64
	s_and_b32 s1, s58, -8
	s_cmp_eq_u32 s1, 8
	v_mfma_f32_16x16x32_bf16 v[72:75], v[52:55], v[76:79], v[72:75]
	ds_read_b128 v[76:79], v167
	s_cselect_b32 s1, 2, 4
	s_cmp_gt_u32 s58, 7
	s_waitcnt lgkmcnt(0)
	v_mfma_f32_16x16x32_bf16 v[76:79], v[56:59], v[76:79], 0
	ds_read_b128 v[84:87], v168 offset:64
	s_cselect_b32 s4, s1, 0
	s_lshr_b32 s8, s0, s4
	v_mfma_f32_16x16x32_bf16 v[76:79], v[52:55], v[80:83], v[76:79]
	ds_read_b128 v[80:83], v168
	s_lshr_b32 s0, s8, 7
	s_add_i32 s0, s0, -1
	s_waitcnt lgkmcnt(0)
	v_mfma_f32_16x16x32_bf16 v[80:83], v[56:59], v[80:83], 0
	ds_read_b128 v[88:91], v169 offset:64
	s_and_b32 s0, s0, s6
	s_lshl_b32 s5, s0, 7
	v_mfma_f32_16x16x32_bf16 v[80:83], v[52:55], v[84:87], v[80:83]
	ds_read_b128 v[84:87], v169
	s_mul_i32 s0, s58, 0x210
	ds_read_b128 v[176:179], v170 offset:64
	s_waitcnt lgkmcnt(1)
	v_mfma_f32_16x16x32_bf16 v[84:87], v[56:59], v[84:87], 0
	s_add_i32 s7, s0, 0
	v_add_u32_e32 v2, s5, v102
	v_readlane_b32 s0, v254, 49
	v_mfma_f32_16x16x32_bf16 v[84:87], v[52:55], v[88:91], v[84:87]
	ds_read_b128 v[88:91], v170
	v_or_b32_e32 v0, v2, v93
	v_cmp_lt_i32_e32 vcc, -1, v2
	s_waitcnt lgkmcnt(0)
	v_mfma_f32_16x16x32_bf16 v[88:91], v[56:59], v[88:91], 0
	v_readlane_b32 s1, v254, 50
	s_add_i32 s7, s7, 0x1d800
	s_and_b64 s[0:1], s[0:1], vcc
	v_mfma_f32_16x16x32_bf16 v[88:91], v[52:55], v[176:179], v[88:91]
	ds_read_b128 v[176:179], v171
	v_cmp_gt_i32_e64 s[74:75], s8, v0
	s_and_b64 s[18:19], s[0:1], s[74:75]
	s_waitcnt lgkmcnt(0)
	v_mfma_f32_16x16x32_bf16 v[56:59], v[56:59], v[176:179], 0
	ds_read_b128 v[176:179], v171 offset:64
	v_mov_b32_e32 v3, 0xf149f2ca
	s_waitcnt lgkmcnt(0)
	v_mfma_f32_16x16x32_bf16 v[52:55], v[52:55], v[176:179], v[56:59]
	s_nop 3
	v_lshl_add_u32 v57, v115, 2, s7
	ds_read_b32 v184, v57
	ds_read_b32 v185, v57 offset:64
	ds_read_b32 v186, v57 offset:128
	ds_read_b32 v187, v57 offset:192
	ds_read_b32 v188, v57 offset:256
	ds_read_b32 v189, v57 offset:320
	ds_read_b32 v190, v57 offset:384
	ds_read_b32 v191, v57 offset:448
	ds_read_b32 v192, v57 offset:512
	v_lshl_add_u32 v232, v116, 2, s7
	ds_read_b32 v193, v232
	ds_read_b32 v194, v232 offset:64
	ds_read_b32 v196, v232 offset:128
	ds_read_b32 v197, v232 offset:192
	ds_read_b32 v198, v232 offset:256
	ds_read_b32 v199, v232 offset:320
	ds_read_b32 v200, v232 offset:384
	ds_read_b32 v201, v232 offset:448
	ds_read_b32 v202, v232 offset:512
	v_lshl_add_u32 v233, v118, 2, s7
	ds_read_b32 v203, v233
	ds_read_b32 v204, v233 offset:64
	ds_read_b32 v205, v233 offset:128
	ds_read_b32 v206, v233 offset:192
	ds_read_b32 v207, v233 offset:256
	ds_read_b32 v208, v233 offset:320
	ds_read_b32 v209, v233 offset:384
	ds_read_b32 v210, v233 offset:448
	ds_read_b32 v211, v233 offset:512
	v_lshl_add_u32 v232, v120, 2, s7
	ds_read_b32 v212, v232
	ds_read_b32 v213, v232 offset:64
	ds_read_b32 v214, v232 offset:128
	ds_read_b32 v215, v232 offset:192
	ds_read_b32 v216, v232 offset:256
	ds_read_b32 v217, v232 offset:320
	ds_read_b32 v218, v232 offset:384
	ds_read_b32 v219, v232 offset:448
	ds_read_b32 v220, v232 offset:512
	v_mov_b32_e32 v56, 0xf149f2ca
	s_waitcnt lgkmcnt(0)
; __device__ void attn_items(const Params& p, unsigned char* shm) {
;     ...
;         float mx[4], ls[4];
; #pragma unroll
;         for (int i = 0; i < 4; ++i) { const int qi = fq * 4 + i; float m = -3.0e38f;
; #pragma unroll
;             for (int kt = 0; kt < 9; ++kt) { const int rel = 16 * kt + fr - 64 - qi, klat = G.q0 - 64 + 16 * w + 16 * kt + fr;
;                 const bool ok = rel >= -64 && rel <= 64 && klat >= 0 && klat < G.n_lat; const int bi = min(max(rel + 64, 0), 128);
;                 const float v = ok ? s[kt][i] + bs[bi] : -1.0e30f; s[kt][i] = v; m = fmaxf(m, v); }
;             m = fmaxf(m, __shfl_xor(m, 1)); m = fmaxf(m, __shfl_xor(m, 2)); m = fmaxf(m, __shfl_xor(m, 4)); m = fmaxf(m, __shfl_xor(m, 8));
;             float sum = 0.f;
; #pragma unroll
;             for (int kt = 0; kt < 9; ++kt) { const float pv = __expf(s[kt][i] - m); s[kt][i] = pv; sum += pv; }
;             sum += __shfl_xor(sum, 1); sum += __shfl_xor(sum, 2); sum += __shfl_xor(sum, 4); sum += __shfl_xor(sum, 8);
;             mx[i] = m; ls[i] = sum; }
	v_add_f32_e32 v184, v60, v184
	v_cndmask_b32_e64 v56, v56, v184, s[18:19]
	v_add_u32_e32 v0, v2, v127
	s_movk_i32 s0, 0xffef
	v_cmp_lt_i32_e64 s[76:77], s0, v2
	v_cmp_gt_i32_e64 s[78:79], s8, v0
	s_and_b64 s[62:63], s[76:77], s[78:79]
	v_add_f32_e32 v185, v64, v185
	v_cndmask_b32_e64 v3, v3, v185, s[62:63]
	v_add_u32_e32 v0, v2, v129
	s_movk_i32 s0, 0xffdf
	v_cmp_lt_i32_e64 s[76:77], s0, v2
	v_cmp_gt_i32_e64 s[78:79], s8, v0
	s_and_b64 s[64:65], s[76:77], s[78:79]
	v_mov_b32_e32 v58, 0xf149f2ca
	v_mov_b32_e32 v59, 0xf149f2ca
	v_add_f32_e32 v186, v68, v186
	v_cndmask_b32_e64 v59, v59, v186, s[64:65]
	v_add_u32_e32 v0, v2, v132
	s_movk_i32 s0, 0xffcf
	v_cmp_lt_i32_e64 s[76:77], s0, v2
	v_cmp_gt_i32_e64 s[78:79], s8, v0
	s_and_b64 s[66:67], s[76:77], s[78:79]
	v_add_f32_e32 v187, v72, v187
	v_cndmask_b32_e64 v58, v58, v187, s[66:67]
	v_add_u32_e32 v0, s5, v99
	v_or_b32_e32 v60, v0, v93
	v_cmp_lt_i32_e64 s[76:77], -1, v0
	v_cmp_gt_i32_e64 s[78:79], s8, v60
	s_and_b64 s[68:69], s[76:77], s[78:79]
	v_mov_b32_e32 v60, 0xf149f2ca
	v_mov_b32_e32 v64, 0xf149f2ca
	v_add_f32_e32 v188, v76, v188
	v_cndmask_b32_e64 v64, v64, v188, s[68:69]
	v_add_u32_e32 v68, v2, v150
	s_movk_i32 s0, 0xffaf
	v_cmp_lt_i32_e64 s[76:77], s0, v2
	v_cmp_gt_i32_e64 s[78:79], s8, v68
	s_and_b64 s[70:71], s[76:77], s[78:79]
	v_add_f32_e32 v189, v80, v189
	v_cndmask_b32_e64 v60, v60, v189, s[70:71]
	v_add_u32_e32 v68, v2, v151
	s_movk_i32 s0, 0xff9f
	v_cmp_lt_i32_e64 s[76:77], s0, v2
	v_cmp_gt_i32_e64 s[78:79], s8, v68
	s_and_b64 s[72:73], s[76:77], s[78:79]
	v_mov_b32_e32 v72, 0xf149f2ca
	v_mov_b32_e32 v76, 0xf149f2ca
	v_add_f32_e32 v190, v84, v190
	v_cndmask_b32_e64 v76, v76, v190, s[72:73]
	v_add_u32_e32 v68, v2, v152
	s_movk_i32 s0, 0xff8f
	v_cmp_lt_i32_e64 s[76:77], s0, v2
	v_cmp_gt_i32_e64 s[78:79], s8, v68
	s_and_b64 s[38:39], s[76:77], s[78:79]
	v_add_f32_e32 v191, v88, v191
	v_cndmask_b32_e64 v72, v72, v191, s[38:39]
	v_readlane_b32 s0, v254, 37
	v_add_u32_e32 v68, v2, v153
	v_cmp_lt_i32_e64 s[76:77], s23, v2
	v_readlane_b32 s1, v254, 38
	s_and_b64 s[0:1], s[0:1], s[76:77]
	v_cmp_gt_i32_e64 s[78:79], s8, v68
	s_and_b64 s[8:9], s[0:1], s[78:79]
	v_mov_b32_e32 v68, 0xf149f2ca
	v_mov_b32_e32 v84, 0xf149f2ca
	v_add_f32_e32 v192, v52, v192
	v_cndmask_b32_e64 v84, v84, v192, s[8:9]
	v_max_f32_e32 v2, v56, v56
	v_max_f32_e32 v2, 0xff61b1e6, v2
	v_max3_f32 v2, v2, v3, v59
	v_max3_f32 v2, v2, v58, v64
	v_max3_f32 v2, v2, v60, v76
	v_max3_f32 v2, v2, v72, v84
	s_nop 1
	v_mov_b32_dpp v52, v2 quad_perm:[1,0,3,2] row_mask:0xf bank_mask:0xf
	v_readlane_b32 s0, v255, 0
	v_readlane_b32 s1, v255, 1
	s_and_b64 s[0:1], s[0:1], vcc
	s_and_b64 s[8:9], s[0:1], s[74:75]
	s_waitcnt lgkmcnt(0)
	v_max_f32_e32 v52, v52, v52
	v_max_f32_e32 v2, v2, v52
	s_nop 1
	v_mov_b32_dpp v52, v2 quad_perm:[2,3,0,1] row_mask:0xf bank_mask:0xf
	s_waitcnt lgkmcnt(0)
	v_max_f32_e32 v52, v52, v52
	v_max_f32_e32 v2, v2, v52
	s_nop 1
	v_mov_b32_dpp v52, v2 row_shl:4 row_mask:0xf bank_mask:0x5
	v_mov_b32_dpp v52, v2 row_shr:4 row_mask:0xf bank_mask:0xa
	s_waitcnt lgkmcnt(0)
	v_max_f32_e32 v52, v52, v52
	v_max_f32_e32 v2, v2, v52
	s_nop 1
	v_mov_b32_dpp v52, v2 row_shl:8 row_mask:0xf bank_mask:0x3
	v_mov_b32_dpp v52, v2 row_shr:8 row_mask:0xf bank_mask:0xc
	s_waitcnt lgkmcnt(0)
	v_max_f32_e32 v52, v52, v52
	v_max_f32_e32 v2, v2, v52
	v_sub_f32_e32 v52, v56, v2
	v_sub_f32_e32 v3, v3, v2
	v_mul_f32_e32 v52, 0x3fb8aa3b, v52
	v_sub_f32_e32 v56, v59, v2
	v_mul_f32_e32 v3, 0x3fb8aa3b, v3
	v_exp_f32_e32 v80, v52
	v_sub_f32_e32 v57, v58, v2
	v_sub_f32_e32 v59, v60, v2
	v_sub_f32_e32 v60, v76, v2
	v_mul_f32_e32 v56, 0x3fb8aa3b, v56
	v_exp_f32_e32 v76, v3
	v_sub_f32_e32 v58, v64, v2
	v_mul_f32_e32 v57, 0x3fb8aa3b, v57
	v_exp_f32_e32 v64, v56
	v_mul_f32_e32 v58, 0x3fb8aa3b, v58
	v_mul_f32_e32 v88, 0x3fb8aa3b, v60
	v_exp_f32_e32 v60, v57
	v_mul_f32_e32 v59, 0x3fb8aa3b, v59
	v_exp_f32_e32 v57, v58
	v_add_f32_e32 v3, 0, v80
	v_sub_f32_e32 v72, v72, v2
	v_exp_f32_e32 v56, v59
	v_add_f32_e32 v3, v76, v3
	v_exp_f32_e32 v52, v88
	v_add_f32_e32 v3, v64, v3
	v_mul_f32_e32 v58, 0x3fb8aa3b, v72
	v_sub_f32_e32 v59, v84, v2
	v_add_f32_e32 v3, v60, v3
	v_exp_f32_e32 v58, v58
	v_mul_f32_e32 v59, 0x3fb8aa3b, v59
	v_add_f32_e32 v3, v57, v3
	v_exp_f32_e32 v59, v59
	v_add_f32_e32 v3, v56, v3
	v_add_f32_e32 v3, v52, v3
	v_add_f32_e32 v3, v58, v3
	v_add_f32_e32 v3, v59, v3
	s_nop 1
	v_mov_b32_dpp v72, v3 quad_perm:[1,0,3,2] row_mask:0xf bank_mask:0xf
	s_waitcnt lgkmcnt(0)
	v_add_f32_e32 v3, v3, v72
	s_nop 1
	v_mov_b32_dpp v72, v3 quad_perm:[2,3,0,1] row_mask:0xf bank_mask:0xf
	s_waitcnt lgkmcnt(0)
	v_add_f32_e32 v3, v3, v72
	s_nop 1
	v_mov_b32_dpp v72, v3 row_shl:4 row_mask:0xf bank_mask:0x5
	v_mov_b32_dpp v72, v3 row_shr:4 row_mask:0xf bank_mask:0xa
	s_waitcnt lgkmcnt(0)
	v_add_f32_e32 v176, v3, v72
	s_nop 1
	v_mov_b32_dpp v177, v176 row_shl:8 row_mask:0xf bank_mask:0x3
	v_mov_b32_dpp v177, v176 row_shr:8 row_mask:0xf bank_mask:0xc
	v_lshl_add_u32 v3, v116, 2, s7
	v_add_f32_e32 v193, v61, v193
	v_cndmask_b32_e64 v68, v68, v193, s[8:9]
	v_mov_b32_e32 v61, 0xf149f2ca
	v_mov_b32_e32 v72, 0xf149f2ca
	v_add_f32_e32 v194, v65, v194
	v_cndmask_b32_e64 v72, v72, v194, s[62:63]
	v_add_f32_e32 v196, v69, v196
	v_cndmask_b32_e64 v61, v61, v196, s[64:65]
	v_mov_b32_e32 v65, 0xf149f2ca
	v_mov_b32_e32 v69, 0xf149f2ca
	v_add_f32_e32 v197, v73, v197
	v_cndmask_b32_e64 v69, v69, v197, s[66:67]
	v_add_f32_e32 v198, v77, v198
	v_cndmask_b32_e64 v65, v65, v198, s[68:69]
	v_mov_b32_e32 v73, 0xf149f2ca
	v_mov_b32_e32 v84, 0xf149f2ca
	v_add_f32_e32 v199, v81, v199
	v_cndmask_b32_e64 v84, v84, v199, s[70:71]
	v_add_f32_e32 v200, v85, v200
	v_cndmask_b32_e64 v73, v73, v200, s[72:73]
	v_mov_b32_e32 v77, 0xf149f2ca
	v_mov_b32_e32 v81, 0xf149f2ca
	v_add_f32_e32 v201, v89, v201
	v_cndmask_b32_e64 v81, v81, v201, s[38:39]
	v_readlane_b32 s0, v255, 2
	v_readlane_b32 s1, v255, 3
	s_and_b64 s[0:1], s[0:1], s[76:77]
	s_and_b64 s[8:9], s[0:1], s[78:79]
	v_add_f32_e32 v202, v53, v202
	v_cndmask_b32_e64 v77, v77, v202, s[8:9]
	v_max_f32_e32 v3, v68, v68
	v_max_f32_e32 v3, 0xff61b1e6, v3
	v_max3_f32 v3, v3, v72, v61
	v_max3_f32 v3, v3, v69, v65
	v_max3_f32 v3, v3, v84, v73
	v_max3_f32 v3, v3, v81, v77
	s_nop 1
	v_mov_b32_dpp v53, v3 quad_perm:[1,0,3,2] row_mask:0xf bank_mask:0xf
	v_readlane_b32 s0, v255, 4
	v_readlane_b32 s1, v255, 5
	s_and_b64 s[0:1], s[0:1], vcc
	s_and_b64 s[8:9], s[0:1], s[74:75]
	s_waitcnt lgkmcnt(0)
; __device__ void attn_items(const Params& p, unsigned char* shm) {
;     ...
;         for (int i = 0; i < 4; ++i) { const int qi = fq * 4 + i; float m = -3.0e38f;
; #pragma unroll
;             for (int kt = 0; kt < 9; ++kt) { const int rel = 16 * kt + fr - 64 - qi, klat = G.q0 - 64 + 16 * w + 16 * kt + fr;
;                 const bool ok = rel >= -64 && rel <= 64 && klat >= 0 && klat < G.n_lat; const int bi = min(max(rel + 64, 0), 128);
;                 const float v = ok ? s[kt][i] + bs[bi] : -1.0e30f; s[kt][i] = v; m = fmaxf(m, v); }
;             m = fmaxf(m, __shfl_xor(m, 1)); m = fmaxf(m, __shfl_xor(m, 2)); m = fmaxf(m, __shfl_xor(m, 4)); m = fmaxf(m, __shfl_xor(m, 8));
;             float sum = 0.f;
; #pragma unroll
;             for (int kt = 0; kt < 9; ++kt) { const float pv = __expf(s[kt][i] - m); s[kt][i] = pv; sum += pv; }
;             sum += __shfl_xor(sum, 1); sum += __shfl_xor(sum, 2); sum += __shfl_xor(sum, 4); sum += __shfl_xor(sum, 8);
;             mx[i] = m; ls[i] = sum; }
	v_max_f32_e32 v53, v53, v53
	v_max_f32_e32 v3, v3, v53
	s_nop 1
	v_mov_b32_dpp v53, v3 quad_perm:[2,3,0,1] row_mask:0xf bank_mask:0xf
	s_waitcnt lgkmcnt(0)
	v_max_f32_e32 v53, v53, v53
	v_max_f32_e32 v3, v3, v53
	s_nop 1
	v_mov_b32_dpp v53, v3 row_shl:4 row_mask:0xf bank_mask:0x5
	v_mov_b32_dpp v53, v3 row_shr:4 row_mask:0xf bank_mask:0xa
	s_waitcnt lgkmcnt(0)
	v_max_f32_e32 v53, v53, v53
	v_max_f32_e32 v3, v3, v53
	s_nop 1
	v_mov_b32_dpp v53, v3 row_shl:8 row_mask:0xf bank_mask:0x3
	v_mov_b32_dpp v53, v3 row_shr:8 row_mask:0xf bank_mask:0xc
	s_waitcnt lgkmcnt(0)
	v_max_f32_e32 v53, v53, v53
	v_max_f32_e32 v3, v3, v53
	v_sub_f32_e32 v53, v68, v3
	v_sub_f32_e32 v68, v72, v3
	v_mul_f32_e32 v53, 0x3fb8aa3b, v53
	v_sub_f32_e32 v61, v61, v3
	v_mul_f32_e32 v68, 0x3fb8aa3b, v68
	v_exp_f32_e32 v97, v53
	v_sub_f32_e32 v69, v69, v3
	v_mul_f32_e32 v61, 0x3fb8aa3b, v61
	v_exp_f32_e32 v89, v68
	v_sub_f32_e32 v65, v65, v3
	v_mul_f32_e32 v69, 0x3fb8aa3b, v69
	v_exp_f32_e32 v88, v61
	v_sub_f32_e32 v72, v84, v3
	v_mul_f32_e32 v65, 0x3fb8aa3b, v65
	v_exp_f32_e32 v85, v69
	v_sub_f32_e32 v73, v73, v3
	v_sub_f32_e32 v81, v81, v3
	v_mul_f32_e32 v72, 0x3fb8aa3b, v72
	v_exp_f32_e32 v65, v65
	v_add_f32_e32 v68, 0, v97
	v_mul_f32_e32 v73, 0x3fb8aa3b, v73
	v_exp_f32_e32 v61, v72
	v_add_f32_e32 v68, v89, v68
	v_mul_f32_e32 v69, 0x3fb8aa3b, v81
	v_exp_f32_e32 v53, v73
	v_add_f32_e32 v68, v88, v68
	v_exp_f32_e32 v81, v69
	v_sub_f32_e32 v69, v77, v3
	v_add_f32_e32 v68, v85, v68
	v_mul_f32_e32 v69, 0x3fb8aa3b, v69
	v_add_f32_e32 v68, v65, v68
	v_exp_f32_e32 v84, v69
	v_add_f32_e32 v68, v61, v68
	v_add_f32_e32 v68, v53, v68
	v_add_f32_e32 v68, v81, v68
	v_add_f32_e32 v68, v84, v68
	s_nop 1
	v_mov_b32_dpp v69, v68 quad_perm:[1,0,3,2] row_mask:0xf bank_mask:0xf
	v_mov_b32_e32 v72, 0xf149f2ca
	v_lshl_add_u32 v77, v118, 2, s7
	v_mov_b32_e32 v73, 0xf149f2ca
	s_waitcnt lgkmcnt(0)
	v_add_f32_e32 v68, v68, v69
	s_nop 1
	v_mov_b32_dpp v69, v68 quad_perm:[2,3,0,1] row_mask:0xf bank_mask:0xf
	s_waitcnt lgkmcnt(0)
	v_add_f32_e32 v68, v68, v69
	s_nop 1
	v_mov_b32_dpp v69, v68 row_shl:4 row_mask:0xf bank_mask:0x5
	v_mov_b32_dpp v69, v68 row_shr:4 row_mask:0xf bank_mask:0xa
	s_waitcnt lgkmcnt(0)
	v_add_f32_e32 v68, v68, v69
	s_nop 1
	v_mov_b32_dpp v69, v68 row_shl:8 row_mask:0xf bank_mask:0x3
	v_mov_b32_dpp v69, v68 row_shr:8 row_mask:0xf bank_mask:0xc
	v_add_f32_e32 v203, v62, v203
	v_cndmask_b32_e64 v73, v73, v203, s[8:9]
	v_add_f32_e32 v204, v66, v204
	v_cndmask_b32_e64 v72, v72, v204, s[62:63]
	v_mov_b32_e32 v62, 0xf149f2ca
	v_mov_b32_e32 v66, 0xf149f2ca
	v_add_f32_e32 v205, v70, v205
	v_cndmask_b32_e64 v66, v66, v205, s[64:65]
	v_add_f32_e32 v206, v74, v206
	v_cndmask_b32_e64 v62, v62, v206, s[66:67]
	v_mov_b32_e32 v74, 0xf149f2ca
	v_mov_b32_e32 v178, 0xf149f2ca
	v_add_f32_e32 v207, v78, v207
	v_cndmask_b32_e64 v178, v178, v207, s[68:69]
	v_add_f32_e32 v208, v82, v208
	v_cndmask_b32_e64 v74, v74, v208, s[70:71]
	v_mov_b32_e32 v78, 0xf149f2ca
	v_mov_b32_e32 v82, 0xf149f2ca
	v_add_f32_e32 v209, v86, v209
	v_cndmask_b32_e64 v82, v82, v209, s[72:73]
	v_add_f32_e32 v210, v90, v210
	v_cndmask_b32_e64 v78, v78, v210, s[38:39]
	v_readlane_b32 s0, v255, 6
	v_readlane_b32 s1, v255, 7
	s_and_b64 s[0:1], s[0:1], s[76:77]
	s_and_b64 s[8:9], s[0:1], s[78:79]
	v_mov_b32_e32 v77, 0xf149f2ca
	v_mov_b32_e32 v180, 0xf149f2ca
	v_add_f32_e32 v211, v54, v211
	v_cndmask_b32_e64 v180, v180, v211, s[8:9]
	v_max_f32_e32 v54, v73, v73
	v_max_f32_e32 v54, 0xff61b1e6, v54
	v_max3_f32 v54, v54, v72, v66
	v_max3_f32 v54, v54, v62, v178
	v_max3_f32 v54, v54, v74, v82
	v_max3_f32 v54, v54, v78, v180
	s_nop 1
	v_mov_b32_dpp v70, v54 quad_perm:[1,0,3,2] row_mask:0xf bank_mask:0xf
	v_readlane_b32 s0, v255, 12
	v_readlane_b32 s1, v255, 13
	s_and_b64 s[0:1], s[0:1], vcc
	s_and_b64 s[8:9], s[0:1], s[74:75]
	s_waitcnt lgkmcnt(0)
	v_max_f32_e32 v70, v70, v70
	v_max_f32_e32 v54, v54, v70
	s_nop 1
	v_mov_b32_dpp v70, v54 quad_perm:[2,3,0,1] row_mask:0xf bank_mask:0xf
	s_waitcnt lgkmcnt(0)
	v_max_f32_e32 v70, v70, v70
	v_max_f32_e32 v54, v54, v70
	s_nop 1
	v_mov_b32_dpp v70, v54 row_shl:4 row_mask:0xf bank_mask:0x5
	v_mov_b32_dpp v70, v54 row_shr:4 row_mask:0xf bank_mask:0xa
	s_waitcnt lgkmcnt(0)
	v_max_f32_e32 v70, v70, v70
	v_max_f32_e32 v54, v54, v70
	s_nop 1
	v_mov_b32_dpp v70, v54 row_shl:8 row_mask:0xf bank_mask:0x3
	v_mov_b32_dpp v70, v54 row_shr:8 row_mask:0xf bank_mask:0xc
	s_waitcnt lgkmcnt(0)
	v_max_f32_e32 v70, v70, v70
	v_max_f32_e32 v70, v54, v70
	v_sub_f32_e32 v54, v73, v70
	v_sub_f32_e32 v72, v72, v70
	v_mul_f32_e32 v54, 0x3fb8aa3b, v54
	v_sub_f32_e32 v66, v66, v70
	v_mul_f32_e32 v72, 0x3fb8aa3b, v72
	v_exp_f32_e32 v179, v54
	v_sub_f32_e32 v62, v62, v70
	v_sub_f32_e32 v73, v178, v70
	v_mul_f32_e32 v66, 0x3fb8aa3b, v66
	v_exp_f32_e32 v178, v72
	v_mul_f32_e32 v62, 0x3fb8aa3b, v62
	v_exp_f32_e32 v90, v66
	v_sub_f32_e32 v74, v74, v70
	v_mul_f32_e32 v73, 0x3fb8aa3b, v73
	v_exp_f32_e32 v86, v62
	v_sub_f32_e32 v82, v82, v70
	v_sub_f32_e32 v78, v78, v70
	v_mul_f32_e32 v74, 0x3fb8aa3b, v74
	v_exp_f32_e32 v66, v73
	v_add_f32_e32 v72, 0, v179
	v_mul_f32_e32 v82, 0x3fb8aa3b, v82
	v_exp_f32_e32 v62, v74
	v_add_f32_e32 v72, v178, v72
	v_mul_f32_e32 v73, 0x3fb8aa3b, v78
	v_exp_f32_e32 v54, v82
	v_add_f32_e32 v72, v90, v72
	v_exp_f32_e32 v78, v73
	v_sub_f32_e32 v73, v180, v70
	v_add_f32_e32 v72, v86, v72
	v_mul_f32_e32 v73, 0x3fb8aa3b, v73
	v_add_f32_e32 v72, v66, v72
	v_exp_f32_e32 v82, v73
	v_add_f32_e32 v72, v62, v72
	v_add_f32_e32 v72, v54, v72
	v_add_f32_e32 v72, v78, v72
	v_add_f32_e32 v72, v82, v72
	s_nop 1
	v_mov_b32_dpp v73, v72 quad_perm:[1,0,3,2] row_mask:0xf bank_mask:0xf
	v_lshl_add_u32 v74, v120, 2, s7
	s_waitcnt lgkmcnt(0)
; __device__ __forceinline__ bf16_t f2bf(float f) { return (bf16_t)(cvt_pk_bf16(f, 0.f) & 0xffffu); }
; __device__ void attn_items(const Params& p, unsigned char* shm) {
;     ...
;         for (int i = 0; i < 4; ++i) { const int qi = fq * 4 + i; float m = -3.0e38f;
; #pragma unroll
;             for (int kt = 0; kt < 9; ++kt) { const int rel = 16 * kt + fr - 64 - qi, klat = G.q0 - 64 + 16 * w + 16 * kt + fr;
;                 const bool ok = rel >= -64 && rel <= 64 && klat >= 0 && klat < G.n_lat; const int bi = min(max(rel + 64, 0), 128);
;                 const float v = ok ? s[kt][i] + bs[bi] : -1.0e30f; s[kt][i] = v; m = fmaxf(m, v); }
;             m = fmaxf(m, __shfl_xor(m, 1)); m = fmaxf(m, __shfl_xor(m, 2)); m = fmaxf(m, __shfl_xor(m, 4)); m = fmaxf(m, __shfl_xor(m, 8));
;             float sum = 0.f;
; #pragma unroll
;             for (int kt = 0; kt < 9; ++kt) { const float pv = __expf(s[kt][i] - m); s[kt][i] = pv; sum += pv; }
;             sum += __shfl_xor(sum, 1); sum += __shfl_xor(sum, 2); sum += __shfl_xor(sum, 4); sum += __shfl_xor(sum, 8);
;             mx[i] = m; ls[i] = sum; }
;         bf16_t* Pw = Ps + w * 16 * 168;
; #pragma unroll
;         for (int i = 0; i < 4; ++i) {
; #pragma unroll
;             for (int kt = 0; kt < 9; ++kt) Pw[(fq * 4 + i) * 168 + 16 * kt + fr] = f2bf(s[kt][i]);
;             Pw[(fq * 4 + i) * 168 + 144 + fr] = 0; }
	v_add_f32_e32 v72, v72, v73
	s_nop 1
	v_mov_b32_dpp v73, v72 quad_perm:[2,3,0,1] row_mask:0xf bank_mask:0xf
	s_waitcnt lgkmcnt(0)
	v_add_f32_e32 v72, v72, v73
	s_nop 1
	v_mov_b32_dpp v73, v72 row_shl:4 row_mask:0xf bank_mask:0x5
	v_mov_b32_dpp v73, v72 row_shr:4 row_mask:0xf bank_mask:0xa
	s_waitcnt lgkmcnt(0)
	v_add_f32_e32 v72, v72, v73
	s_nop 1
	v_mov_b32_dpp v73, v72 row_shl:8 row_mask:0xf bank_mask:0x3
	v_mov_b32_dpp v73, v72 row_shr:8 row_mask:0xf bank_mask:0xc
	v_add_f32_e32 v212, v63, v212
	v_cndmask_b32_e64 v77, v77, v212, s[8:9]
	v_mov_b32_e32 v181, 0xf149f2ca
	v_mov_b32_e32 v183, 0xf149f2ca
	v_add_f32_e32 v213, v67, v213
	v_cndmask_b32_e64 v183, v183, v213, s[62:63]
	v_add_f32_e32 v214, v71, v214
	v_cndmask_b32_e64 v181, v181, v214, s[64:65]
	v_mov_b32_e32 v180, 0xf149f2ca
	v_mov_b32_e32 v182, 0xf149f2ca
	v_add_f32_e32 v215, v75, v215
	v_cndmask_b32_e64 v182, v182, v215, s[66:67]
	v_add_f32_e32 v216, v79, v216
	v_cndmask_b32_e64 v180, v180, v216, s[68:69]
	v_mov_b32_e32 v75, 0xf149f2ca
	v_mov_b32_e32 v79, 0xf149f2ca
	v_add_f32_e32 v217, v83, v217
	v_cndmask_b32_e64 v79, v79, v217, s[70:71]
	v_add_f32_e32 v218, v87, v218
	v_cndmask_b32_e64 v75, v75, v218, s[72:73]
	v_mov_b32_e32 v63, 0xf149f2ca
	v_mov_b32_e32 v67, 0xf149f2ca
	v_add_f32_e32 v219, v91, v219
	v_cndmask_b32_e64 v67, v67, v219, s[38:39]
	v_readlane_b32 s0, v255, 8
	v_readlane_b32 s1, v255, 9
	s_and_b64 s[0:1], s[0:1], s[76:77]
	s_and_b64 s[8:9], s[0:1], s[78:79]
	v_add_f32_e32 v220, v55, v220
	v_cndmask_b32_e64 v63, v63, v220, s[8:9]
	v_max_f32_e32 v55, v77, v77
	v_max_f32_e32 v55, 0xff61b1e6, v55
	v_max3_f32 v55, v55, v183, v181
	v_max3_f32 v55, v55, v182, v180
	v_max3_f32 v55, v55, v79, v75
	v_max3_f32 v55, v55, v67, v63
	s_nop 1
	v_mov_b32_dpp v71, v55 quad_perm:[1,0,3,2] row_mask:0xf bank_mask:0xf
	v_cvt_pk_bf16_f32 v52, v52, v1
	ds_write_b16 v172, v52 offset:192
	v_cvt_pk_bf16_f32 v52, v58, v1
	ds_write_b16 v172, v52 offset:224
	s_waitcnt lgkmcnt(2)
	v_max_f32_e32 v71, v71, v71
	v_max_f32_e32 v55, v55, v71
	s_nop 1
	v_mov_b32_dpp v71, v55 quad_perm:[2,3,0,1] row_mask:0xf bank_mask:0xf
	v_cvt_pk_bf16_f32 v52, v59, v1
	v_cvt_pk_bf16_f32 v80, v80, v1
	ds_write_b16 v172, v80
	v_cvt_pk_bf16_f32 v76, v76, v1
	s_waitcnt lgkmcnt(1)
	v_max_f32_e32 v71, v71, v71
	v_max_f32_e32 v55, v55, v71
	s_nop 1
	v_mov_b32_dpp v71, v55 row_shl:4 row_mask:0xf bank_mask:0x5
	v_mov_b32_dpp v71, v55 row_shr:4 row_mask:0xf bank_mask:0xa
	ds_write_b16 v172, v76 offset:32
	v_cvt_pk_bf16_f32 v64, v64, v1
	ds_write_b16 v172, v64 offset:64
	v_cvt_pk_bf16_f32 v60, v60, v1
	ds_write_b16 v172, v60 offset:96
	v_cvt_pk_bf16_f32 v57, v57, v1
	ds_write_b16 v172, v57 offset:128
	v_cvt_pk_bf16_f32 v56, v56, v1
	ds_write_b16 v172, v56 offset:160
	ds_write_b16 v172, v52 offset:256
	ds_write_b16 v122, v1 offset:288
	v_cvt_pk_bf16_f32 v52, v97, v1
	ds_write_b16 v175, v52
	v_cvt_pk_bf16_f32 v52, v89, v1
	ds_write_b16 v175, v52 offset:32
	v_cvt_pk_bf16_f32 v52, v88, v1
	ds_write_b16 v175, v52 offset:64
	v_cvt_pk_bf16_f32 v52, v85, v1
	s_waitcnt lgkmcnt(10)
	v_max_f32_e32 v71, v71, v71
	ds_write_b16 v175, v52 offset:96
	v_cvt_pk_bf16_f32 v52, v65, v1
	v_max_f32_e32 v55, v55, v71
	ds_write_b16 v175, v52 offset:128
	v_cvt_pk_bf16_f32 v52, v61, v1
	s_nop 1
	v_mov_b32_dpp v71, v55 row_shl:8 row_mask:0xf bank_mask:0x3
	v_mov_b32_dpp v71, v55 row_shr:8 row_mask:0xf bank_mask:0xc
	ds_write_b16 v175, v52 offset:160
	v_cvt_pk_bf16_f32 v52, v53, v1
	ds_write_b16 v175, v52 offset:192
	v_cvt_pk_bf16_f32 v52, v81, v1
	ds_write_b16 v175, v52 offset:224
	v_cvt_pk_bf16_f32 v52, v84, v1
	ds_write_b16 v175, v52 offset:256
	ds_write_b16 v123, v1 offset:288
	v_cvt_pk_bf16_f32 v52, v179, v1
	ds_write_b16 v175, v52 offset:336
	v_cvt_pk_bf16_f32 v52, v178, v1
	s_waitcnt lgkmcnt(6)
	v_max_f32_e32 v71, v71, v71
	ds_write_b16 v175, v52 offset:368
	v_cvt_pk_bf16_f32 v52, v90, v1
	v_max_f32_e32 v71, v55, v71
	ds_write_b16 v175, v52 offset:400
	v_cvt_pk_bf16_f32 v52, v86, v1
	v_sub_f32_e32 v55, v77, v71
	ds_write_b16 v175, v52 offset:432
	v_cvt_pk_bf16_f32 v52, v66, v1
	v_mul_f32_e32 v55, 0x3fb8aa3b, v55
	v_sub_f32_e32 v83, v183, v71
	ds_write_b16 v175, v52 offset:464
	v_cvt_pk_bf16_f32 v52, v62, v1
	v_exp_f32_e32 v55, v55
	v_mul_f32_e32 v83, 0x3fb8aa3b, v83
	v_sub_f32_e32 v87, v181, v71
	ds_write_b16 v175, v52 offset:496
	v_cvt_pk_bf16_f32 v52, v54, v1
	v_exp_f32_e32 v83, v83
	v_mul_f32_e32 v87, 0x3fb8aa3b, v87
	v_sub_f32_e32 v91, v182, v71
	ds_write_b16 v175, v52 offset:528
	v_cvt_pk_bf16_f32 v52, v78, v1
	v_add_f32_e32 v74, v176, v177
	v_exp_f32_e32 v87, v87
	v_mul_f32_e32 v91, 0x3fb8aa3b, v91
	v_sub_f32_e32 v176, v180, v71
	ds_write_b16 v175, v52 offset:560
	v_cvt_pk_bf16_f32 v52, v82, v1
	v_exp_f32_e32 v91, v91
	v_mul_f32_e32 v176, 0x3fb8aa3b, v176
	v_sub_f32_e32 v79, v79, v71
	ds_write_b16 v175, v52 offset:592
	ds_write_b16 v124, v1 offset:288
	v_cvt_pk_bf16_f32 v52, v55, v1
	v_add_f32_e32 v77, 0, v55
	v_exp_f32_e32 v176, v176
	v_mul_f32_e32 v79, 0x3fb8aa3b, v79
	v_sub_f32_e32 v75, v75, v71
	ds_write_b16 v175, v52 offset:672
	v_cvt_pk_bf16_f32 v52, v83, v1
	v_add_f32_e32 v77, v83, v77
	v_exp_f32_e32 v79, v79
	v_mul_f32_e32 v75, 0x3fb8aa3b, v75
	v_sub_f32_e32 v67, v67, v71
	ds_write_b16 v175, v52 offset:704
	v_cvt_pk_bf16_f32 v52, v87, v1
	v_add_f32_e32 v77, v87, v77
	v_exp_f32_e32 v177, v75
	v_mul_f32_e32 v67, 0x3fb8aa3b, v67
	v_sub_f32_e32 v63, v63, v71
	ds_write_b16 v175, v52 offset:736
	v_cvt_pk_bf16_f32 v52, v91, v1
	v_add_f32_e32 v77, v91, v77
	v_exp_f32_e32 v67, v67
	v_mul_f32_e32 v63, 0x3fb8aa3b, v63
	ds_write_b16 v175, v52 offset:768
	v_cvt_pk_bf16_f32 v52, v176, v1
	v_add_f32_e32 v77, v176, v77
	v_exp_f32_e32 v63, v63
	ds_write_b16 v175, v52 offset:800
	v_cvt_pk_bf16_f32 v52, v79, v1
	v_add_f32_e32 v77, v79, v77
	ds_write_b16 v175, v52 offset:832
	v_cvt_pk_bf16_f32 v52, v177, v1
	v_add_f32_e32 v75, v177, v77
	ds_write_b16 v175, v52 offset:864
	v_cvt_pk_bf16_f32 v52, v67, v1
	v_add_f32_e32 v75, v67, v75
	ds_write_b16 v175, v52 offset:896
	v_cvt_pk_bf16_f32 v52, v63, v1
	v_add_f32_e32 v75, v63, v75
	ds_write_b16 v175, v52 offset:928
	ds_write_b16 v125, v1 offset:288
	s_waitcnt lgkmcnt(0)
; __device__ __forceinline__ bf16_t f2bf(float f) { return (bf16_t)(cvt_pk_bf16(f, 0.f) & 0xffffu); }
; __device__ void attn_items(const Params& p, unsigned char* shm) {
;     ...
;         __syncthreads();
;         f32x4 o[4];
; #pragma unroll
;         for (int nt = 0; nt < 4; ++nt) o[nt] = (f32x4){0.f, 0.f, 0.f, 0.f};
; #pragma unroll
;         for (int ks = 0; ks < 5; ++ks) { const bf16x8 ap = *(const bf16x8*)(Pw + fr * 168 + ks * 32 + fq * 8);
; #pragma unroll
;             for (int nt = 0; nt < 4; ++nt) { const int dim = nt * 16 + fr; o[nt] = __builtin_amdgcn_mfma_f32_16x16x32_bf16(ap, *(const bf16x8*)(Vt + dim * 320 + ((16 * w + ks * 32 + fq * 8) ^ ((dim >> 3) << 3))), o[nt], 0, 0, 0); } }
;         __syncthreads();
; #pragma unroll
;         for (int i = 0; i < 4; ++i) { const float inv = 1.0f / ls[i];
; #pragma unroll
;             for (int nt = 0; nt < 4; ++nt) Pw[(fq * 4 + i) * 168 + nt * 16 + fr] = f2bf(o[nt][i] * inv);
;             if (fr == 0) LSE[(size_t)(G.seq_start + G.r + G.dil * (G.q0 + 16 * w + fq * 4 + i)) * 24 + G.hd] = mx[i] + __logf(ls[i]); }
	ds_read_b128 v[52:55], v107
	ds_read_b128 v[56:59], v126 offset:36864
	ds_read_b128 v[60:63], v128 offset:36864
	ds_read_b128 v[64:67], v131 offset:36864
	ds_read_b128 v[78:81], v133 offset:36864
	s_waitcnt lgkmcnt(3)
	v_mfma_f32_16x16x32_bf16 v[56:59], v[52:55], v[56:59], 0
	s_mul_i32 s0, s58, 0xffffa000
	s_add_i32 s7, s2, s0
	s_and_b64 s[0:1], s[60:61], exec
	s_waitcnt lgkmcnt(2)
	v_mfma_f32_16x16x32_bf16 v[60:63], v[52:55], v[60:63], 0
	s_cselect_b32 s0, 4, 7
	s_sub_i32 s8, s0, s4
	s_and_b32 s7, s7, 0xfffff800
	s_waitcnt lgkmcnt(1)
	v_mfma_f32_16x16x32_bf16 v[64:67], v[52:55], v[64:67], 0
	s_and_b64 s[0:1], s[60:61], exec
	s_cselect_b32 s0, s7, 0x2000
	s_lshr_b32 s1, s6, s8
	s_waitcnt lgkmcnt(0)
	v_mfma_f32_16x16x32_bf16 v[52:55], v[52:55], v[78:81], 0
	ds_read_b128 v[78:81], v107 offset:64
	ds_read_b128 v[82:85], v134 offset:36864
	s_nop 1
	v_mov_b32_dpp v77, v75 quad_perm:[1,0,3,2] row_mask:0xf bank_mask:0xf
	s_ashr_i32 s59, s58, 31
	s_waitcnt lgkmcnt(0)
	v_mfma_f32_16x16x32_bf16 v[56:59], v[78:81], v[82:85], v[56:59]
	ds_read_b128 v[82:85], v135 offset:36864
	s_add_i32 s6, s1, s0
	s_lshl_b64 s[0:1], s[58:59], 2
	s_waitcnt lgkmcnt(0)
	v_mfma_f32_16x16x32_bf16 v[60:63], v[78:81], v[82:85], v[60:63]
	ds_read_b128 v[82:85], v136 offset:36864
	s_mov_b64 s[8:9], s[88:89]
	s_add_u32 s38, s8, s0
	s_waitcnt lgkmcnt(0)
	v_mfma_f32_16x16x32_bf16 v[64:67], v[78:81], v[82:85], v[64:67]
	ds_read_b128 v[82:85], v137 offset:36864
	s_addc_u32 s39, s9, s1
	v_add_f32_e32 v75, v75, v77
	s_waitcnt lgkmcnt(0)
	v_mfma_f32_16x16x32_bf16 v[52:55], v[78:81], v[82:85], v[52:55]
	ds_read_b128 v[78:81], v107 offset:128
	ds_read_b128 v[82:85], v138 offset:36864
	s_nop 1
	v_mov_b32_dpp v77, v75 quad_perm:[2,3,0,1] row_mask:0xf bank_mask:0xf
	v_add_u32_e32 v76, s5, v108
	s_waitcnt lgkmcnt(0)
	v_mfma_f32_16x16x32_bf16 v[56:59], v[78:81], v[82:85], v[56:59]
	ds_read_b128 v[82:85], v139 offset:36864
	s_waitcnt lgkmcnt(1)
	v_add_f32_e32 v75, v75, v77
	s_nop 1
	v_mov_b32_dpp v77, v75 row_shl:4 row_mask:0xf bank_mask:0x5
	v_mov_b32_dpp v77, v75 row_shr:4 row_mask:0xf bank_mask:0xa
	s_waitcnt lgkmcnt(0)
	v_mfma_f32_16x16x32_bf16 v[60:63], v[78:81], v[82:85], v[60:63]
	ds_read_b128 v[82:85], v140 offset:36864
	s_waitcnt lgkmcnt(1)
	v_add_f32_e32 v75, v75, v77
	s_nop 1
	v_mov_b32_dpp v77, v75 row_shl:8 row_mask:0xf bank_mask:0x3
	v_mov_b32_dpp v77, v75 row_shr:8 row_mask:0xf bank_mask:0xc
	s_waitcnt lgkmcnt(0)
	v_mfma_f32_16x16x32_bf16 v[64:67], v[78:81], v[82:85], v[64:67]
	ds_read_b128 v[82:85], v141 offset:36864
	s_waitcnt lgkmcnt(0)
	v_mfma_f32_16x16x32_bf16 v[78:81], v[78:81], v[82:85], v[52:55]
	ds_read_b128 v[82:85], v107 offset:192
	s_nop 1
	ds_read_b128 v[52:55], v142 offset:36864
	s_waitcnt lgkmcnt(0)
	v_mfma_f32_16x16x32_bf16 v[52:55], v[82:85], v[52:55], v[56:59]
	s_nop 2
	ds_read_b128 v[56:59], v143 offset:36864
	s_waitcnt lgkmcnt(0)
	v_mfma_f32_16x16x32_bf16 v[56:59], v[82:85], v[56:59], v[60:63]
	s_nop 2
	ds_read_b128 v[60:63], v144 offset:36864
	s_waitcnt lgkmcnt(0)
	v_mfma_f32_16x16x32_bf16 v[60:63], v[82:85], v[60:63], v[64:67]
	s_nop 2
	ds_read_b128 v[64:67], v145 offset:36864
	s_waitcnt lgkmcnt(0)
	v_mfma_f32_16x16x32_bf16 v[64:67], v[82:85], v[64:67], v[78:81]
	s_nop 2
	ds_read_b128 v[78:81], v107 offset:256
	ds_read_b128 v[82:85], v130 offset:36864
	s_waitcnt lgkmcnt(0)
	v_mfma_f32_16x16x32_bf16 v[52:55], v[78:81], v[82:85], v[52:55]
	ds_read_b128 v[82:85], v146 offset:36864
	s_waitcnt lgkmcnt(0)
	v_mfma_f32_16x16x32_bf16 v[56:59], v[78:81], v[82:85], v[56:59]
	ds_read_b128 v[82:85], v147 offset:36864
	s_waitcnt lgkmcnt(0)
	v_mfma_f32_16x16x32_bf16 v[60:63], v[78:81], v[82:85], v[60:63]
	ds_read_b128 v[82:85], v148 offset:36864
	s_waitcnt lgkmcnt(0)
	v_mfma_f32_16x16x32_bf16 v[64:67], v[78:81], v[82:85], v[64:67]
	v_div_scale_f32 v78, s[0:1], v74, v74, 1.0
	v_rcp_f32_e32 v79, v78
	s_nop 0
	v_fma_f32 v80, -v78, v79, 1.0
	v_fmac_f32_e32 v79, v80, v79
	v_div_scale_f32 v80, vcc, 1.0, v74, 1.0
	v_mul_f32_e32 v81, v80, v79
	v_fma_f32 v82, -v78, v81, v80
	v_fmac_f32_e32 v81, v82, v79
	v_fma_f32 v78, -v78, v81, v80
	v_div_fmas_f32 v78, v78, v79, v81
	v_div_fixup_f32 v78, v78, v74, 1.0
	v_mul_f32_e32 v52, v78, v52
	v_cvt_pk_bf16_f32 v52, v52, v1
	ds_write_b16 v172, v52
	v_mul_f32_e32 v52, v78, v56
	v_cvt_pk_bf16_f32 v52, v52, v1
	ds_write_b16 v172, v52 offset:32
	v_mul_f32_e32 v52, v78, v60
	v_cvt_pk_bf16_f32 v52, v52, v1
	ds_write_b16 v172, v52 offset:64
	v_mul_f32_e32 v52, v78, v64
	v_cvt_pk_bf16_f32 v52, v52, v1
	ds_write_b16 v172, v52 offset:96
	s_and_saveexec_b64 s[0:1], s[36:37]
	s_cbranch_execz .LBB0_447
	s_mov_b32 s5, 0x800000
	v_cmp_gt_f32_e32 vcc, s5, v74
	s_mov_b32 s5, 0x3f317217
	v_mov_b64_e32 v[78:79], s[38:39]
	v_cndmask_b32_e64 v52, 0, 32, vcc
	v_ldexp_f32 v52, v74, v52
	v_log_f32_e32 v52, v52
	v_cndmask_b32_e32 v56, 0, v231, vcc
	v_mul_f32_e32 v60, 0x3f317217, v52
	v_fma_f32 v60, v52, s5, -v60
	v_fmac_f32_e32 v60, 0x3377d1cf, v52
	s_mov_b32 s5, 0x7f800000
	v_fmac_f32_e32 v60, 0x3f317217, v52
	v_cmp_lt_f32_e64 vcc, |v52|, s5
	s_nop 1
	v_cndmask_b32_e32 v52, v52, v60, vcc
	v_sub_f32_e32 v52, v52, v56
	v_add_f32_e32 v2, v2, v52
	v_lshlrev_b32_e32 v52, s4, v76
	v_add_u32_e32 v52, s6, v52
	v_mad_i64_i32 v[78:79], s[8:9], v52, s82, v[78:79]
	global_store_dword v[78:79], v2, off
